# P4 rotary epilogue: rot-table loads hoisted to block head (no per-store vmcnt serialization)
# speedup vs baseline: 1.0024x; 1.0024x over previous
.LBB0_482:
	s_andn2_b64 vcc, exec, s[0:1]
	s_cbranch_vccnz .LBB0_484
	v_lshlrev_b32_e32 v196, 6, v162
	v_and_b32_e32 v196, 0x1f3c0, v196
	v_mov_b32_e32 v197, 0
	v_lshl_add_u64 v[196:197], v[138:139], 0, v[196:197]
	global_load_dwordx4 v[192:195], v[196:197], off
	s_nop 0
	global_load_dwordx4 v[196:199], v[196:197], off offset:16
	v_lshlrev_b32_e32 v204, 6, v169
	v_and_b32_e32 v204, 0x1f7c0, v204
	v_mov_b32_e32 v205, 0
	v_lshl_add_u64 v[204:205], v[138:139], 0, v[204:205]
	global_load_dwordx4 v[200:203], v[204:205], off
	s_nop 0
	global_load_dwordx4 v[204:207], v[204:205], off offset:16
	v_lshlrev_b32_e32 v212, 6, v168
	v_and_b32_e32 v212, 0x1fbc0, v212
	v_mov_b32_e32 v213, 0
	v_lshl_add_u64 v[212:213], v[138:139], 0, v[212:213]
	global_load_dwordx4 v[208:211], v[212:213], off
	s_nop 0
	global_load_dwordx4 v[212:215], v[212:213], off offset:16
	v_lshlrev_b32_e32 v220, 6, v167
	v_and_b32_e32 v220, 0x1ffc0, v220
	v_mov_b32_e32 v221, 0
	v_lshl_add_u64 v[220:221], v[138:139], 0, v[220:221]
	global_load_dwordx4 v[216:219], v[220:221], off
	s_nop 0
	global_load_dwordx4 v[220:223], v[220:221], off offset:16
	v_lshlrev_b32_e32 v228, 6, v166
	v_and_b32_e32 v228, 0x1f3c0, v228
	v_mov_b32_e32 v229, 0
	v_lshl_add_u64 v[228:229], v[138:139], 0, v[228:229]
	global_load_dwordx4 v[224:227], v[228:229], off
	s_nop 0
	global_load_dwordx4 v[228:231], v[228:229], off offset:16
	v_lshlrev_b32_e32 v236, 6, v165
	v_and_b32_e32 v236, 0x1f7c0, v236
	v_mov_b32_e32 v237, 0
	v_lshl_add_u64 v[236:237], v[138:139], 0, v[236:237]
	global_load_dwordx4 v[232:235], v[236:237], off
	s_nop 0
	global_load_dwordx4 v[236:239], v[236:237], off offset:16
	v_lshlrev_b32_e32 v244, 6, v164
	v_and_b32_e32 v244, 0x1fbc0, v244
	v_mov_b32_e32 v245, 0
	v_lshl_add_u64 v[244:245], v[138:139], 0, v[244:245]
	global_load_dwordx4 v[240:243], v[244:245], off
	s_nop 0
	global_load_dwordx4 v[244:247], v[244:245], off offset:16
	v_lshlrev_b32_e32 v252, 6, v163
	v_and_b32_e32 v252, 0x1ffc0, v252
	v_mov_b32_e32 v253, 0
	v_lshl_add_u64 v[252:253], v[138:139], 0, v[252:253]
	global_load_dwordx4 v[248:251], v[252:253], off
	global_load_dword v183, v[252:253], off offset:24
	global_load_dword v255, v[252:253], off offset:28
	s_nop 0
	global_load_dwordx2 v[252:253], v[252:253], off offset:16
	s_waitcnt vmcnt(0)
	v_ashrrev_i32_e32 v151, 31, v136
	v_mov_b32_e32 v150, v136
	v_lshlrev_b32_e32 v136, 6, v162
	v_and_b32_e32 v136, 0x1f3c0, v136
	v_lshl_add_u64 v[178:179], v[138:139], 0, v[136:137]
	s_nop 1
	v_mov_b32_e32 v170, v192
	v_mov_b32_e32 v171, v193
	v_mov_b32_e32 v172, v194
	v_mov_b32_e32 v173, v195
	v_mov_b32_e32 v174, v196
	v_mov_b32_e32 v175, v197
	v_mov_b32_e32 v176, v198
	v_mov_b32_e32 v177, v199
	v_lshlrev_b64 v[150:151], 1, v[150:151]
	v_lshl_add_u64 v[152:153], v[152:153], 0, v[150:151]
	v_cndmask_b32_e64 v173, 0, v173, s[4:5]
	v_cndmask_b32_e64 v171, 0, v171, s[4:5]
	v_cndmask_b32_e64 v177, 0, v177, s[4:5]
	v_cndmask_b32_e64 v175, 0, v175, s[4:5]
	v_mov_b32_e32 v136, v171
	v_mov_b32_e32 v180, v173
	v_mov_b32_e32 v184, v175
	v_mov_b32_e32 v186, v177
	v_cndmask_b32_e64 v172, 1.0, v172, s[4:5]
	v_cndmask_b32_e64 v170, 1.0, v170, s[4:5]
	v_cndmask_b32_e64 v176, 1.0, v176, s[4:5]
	v_cndmask_b32_e64 v174, 1.0, v174, s[4:5]
	v_pk_mul_f32 v[188:189], v[64:65], v[136:137] op_sel:[1,0] op_sel_hi:[0,0]
	v_pk_mul_f32 v[180:181], v[66:67], v[180:181] op_sel:[1,0] op_sel_hi:[0,0]
	v_pk_mul_f32 v[184:185], v[28:29], v[184:185] op_sel:[1,0] op_sel_hi:[0,0]
	v_pk_mul_f32 v[186:187], v[30:31], v[186:187] op_sel:[1,0] op_sel_hi:[0,0]
	v_pk_fma_f32 v[190:191], v[64:65], v[170:171], v[188:189] neg_lo:[0,0,1] neg_hi:[0,0,1]
	v_pk_fma_f32 v[170:171], v[64:65], v[170:171], v[188:189] op_sel_hi:[1,0,1]
	v_pk_fma_f32 v[188:189], v[66:67], v[172:173], v[180:181] neg_lo:[0,0,1] neg_hi:[0,0,1]
	v_pk_fma_f32 v[172:173], v[66:67], v[172:173], v[180:181] op_sel_hi:[1,0,1]
	v_pk_fma_f32 v[180:181], v[28:29], v[174:175], v[184:185] neg_lo:[0,0,1] neg_hi:[0,0,1]
	v_pk_fma_f32 v[174:175], v[28:29], v[174:175], v[184:185] op_sel_hi:[1,0,1]
	v_pk_fma_f32 v[184:185], v[30:31], v[176:177], v[186:187] neg_lo:[0,0,1] neg_hi:[0,0,1]
	v_pk_fma_f32 v[176:177], v[30:31], v[176:177], v[186:187] op_sel_hi:[1,0,1]
	v_cvt_pk_bf16_f32 v170, v190, v171
	v_cvt_pk_bf16_f32 v171, v188, v173
	v_cvt_pk_bf16_f32 v172, v180, v175
	v_cvt_pk_bf16_f32 v173, v184, v177
	global_store_dwordx4 v[152:153], v[170:173], off
	s_nop 1
	v_mov_b32_e32 v170, v192
	v_mov_b32_e32 v171, v193
	v_mov_b32_e32 v172, v194
	v_mov_b32_e32 v173, v195
	s_nop 0
	v_mov_b32_e32 v174, v196
	v_mov_b32_e32 v175, v197
	v_mov_b32_e32 v176, v198
	v_mov_b32_e32 v177, v199
	v_lshlrev_b32_e32 v136, 6, v169
	v_and_b32_e32 v136, 0x1f7c0, v136
	v_lshl_add_u64 v[178:179], v[138:139], 0, v[136:137]
	v_cndmask_b32_e64 v173, 0, v173, s[4:5]
	v_cndmask_b32_e64 v171, 0, v171, s[4:5]
	v_cndmask_b32_e64 v177, 0, v177, s[4:5]
	v_cndmask_b32_e64 v175, 0, v175, s[4:5]
	v_mov_b32_e32 v136, v171
	v_mov_b32_e32 v180, v173
	v_mov_b32_e32 v184, v175
	v_mov_b32_e32 v186, v177
	v_cndmask_b32_e64 v172, 1.0, v172, s[4:5]
	v_cndmask_b32_e64 v170, 1.0, v170, s[4:5]
	v_cndmask_b32_e64 v176, 1.0, v176, s[4:5]
	v_cndmask_b32_e64 v174, 1.0, v174, s[4:5]
	v_pk_mul_f32 v[188:189], v[124:125], v[136:137] op_sel:[1,0] op_sel_hi:[0,0]
	v_pk_mul_f32 v[180:181], v[126:127], v[180:181] op_sel:[1,0] op_sel_hi:[0,0]
	v_pk_mul_f32 v[184:185], v[120:121], v[184:185] op_sel:[1,0] op_sel_hi:[0,0]
	v_pk_mul_f32 v[186:187], v[122:123], v[186:187] op_sel:[1,0] op_sel_hi:[0,0]
	v_pk_fma_f32 v[190:191], v[124:125], v[170:171], v[188:189] neg_lo:[0,0,1] neg_hi:[0,0,1]
	v_pk_fma_f32 v[124:125], v[124:125], v[170:171], v[188:189] op_sel_hi:[1,0,1]
	v_pk_fma_f32 v[170:171], v[126:127], v[172:173], v[180:181] neg_lo:[0,0,1] neg_hi:[0,0,1]
	v_pk_fma_f32 v[126:127], v[126:127], v[172:173], v[180:181] op_sel_hi:[1,0,1]
	v_pk_fma_f32 v[172:173], v[120:121], v[174:175], v[184:185] neg_lo:[0,0,1] neg_hi:[0,0,1]
	v_pk_fma_f32 v[174:175], v[120:121], v[174:175], v[184:185] op_sel_hi:[1,0,1]
	v_pk_fma_f32 v[180:181], v[122:123], v[176:177], v[186:187] neg_lo:[0,0,1] neg_hi:[0,0,1]
	v_pk_fma_f32 v[122:123], v[122:123], v[176:177], v[186:187] op_sel_hi:[1,0,1]
	v_cvt_pk_bf16_f32 v120, v190, v125
	v_cvt_pk_bf16_f32 v121, v170, v127
	v_cvt_pk_bf16_f32 v122, v172, v175
	v_cvt_pk_bf16_f32 v123, v180, v123
	global_store_dwordx4 v[152:153], v[120:123], off offset:256
	s_nop 1
	v_mov_b32_e32 v122, v200
	v_mov_b32_e32 v123, v201
	v_mov_b32_e32 v124, v202
	v_mov_b32_e32 v125, v203
	s_nop 0
	v_mov_b32_e32 v170, v204
	v_mov_b32_e32 v171, v205
	v_mov_b32_e32 v172, v206
	v_mov_b32_e32 v173, v207
	v_mov_b64_e32 v[120:121], s[10:11]
	v_mad_i64_i32 v[126:127], s[0:1], v169, s68, v[120:121]
	v_lshl_add_u64 v[126:127], v[126:127], 0, v[150:151]
	v_cndmask_b32_e64 v125, 0, v125, s[4:5]
	v_cndmask_b32_e64 v123, 0, v123, s[4:5]
	v_cndmask_b32_e64 v153, 0, v173, s[4:5]
	v_cndmask_b32_e64 v171, 0, v171, s[4:5]
	v_cndmask_b32_e64 v152, 1.0, v172, s[4:5]
	v_mov_b32_e32 v136, v123
	v_mov_b32_e32 v172, v125
	v_mov_b32_e32 v174, v171
	v_mov_b32_e32 v176, v153
	v_cndmask_b32_e64 v124, 1.0, v124, s[4:5]
	v_cndmask_b32_e64 v122, 1.0, v122, s[4:5]
	v_cndmask_b32_e64 v170, 1.0, v170, s[4:5]
	v_pk_mul_f32 v[180:181], v[60:61], v[136:137] op_sel:[1,0] op_sel_hi:[0,0]
	v_pk_mul_f32 v[172:173], v[62:63], v[172:173] op_sel:[1,0] op_sel_hi:[0,0]
	v_pk_mul_f32 v[174:175], v[24:25], v[174:175] op_sel:[1,0] op_sel_hi:[0,0]
	v_pk_mul_f32 v[176:177], v[26:27], v[176:177] op_sel:[1,0] op_sel_hi:[0,0]
	v_pk_fma_f32 v[184:185], v[60:61], v[122:123], v[180:181] neg_lo:[0,0,1] neg_hi:[0,0,1]
	v_pk_fma_f32 v[122:123], v[60:61], v[122:123], v[180:181] op_sel_hi:[1,0,1]
	v_pk_fma_f32 v[180:181], v[62:63], v[124:125], v[172:173] neg_lo:[0,0,1] neg_hi:[0,0,1]
	v_pk_fma_f32 v[124:125], v[62:63], v[124:125], v[172:173] op_sel_hi:[1,0,1]
	v_pk_fma_f32 v[172:173], v[24:25], v[170:171], v[174:175] neg_lo:[0,0,1] neg_hi:[0,0,1]
	v_pk_fma_f32 v[170:171], v[24:25], v[170:171], v[174:175] op_sel_hi:[1,0,1]
	v_pk_fma_f32 v[174:175], v[26:27], v[152:153], v[176:177] neg_lo:[0,0,1] neg_hi:[0,0,1]
	v_pk_fma_f32 v[152:153], v[26:27], v[152:153], v[176:177] op_sel_hi:[1,0,1]
	v_cvt_pk_bf16_f32 v122, v184, v123
	v_cvt_pk_bf16_f32 v123, v180, v125
	v_cvt_pk_bf16_f32 v124, v172, v171
	v_cvt_pk_bf16_f32 v125, v174, v153
	global_store_dwordx4 v[126:127], v[122:125], off
	s_nop 1
	v_mov_b32_e32 v122, v200
	v_mov_b32_e32 v123, v201
	v_mov_b32_e32 v124, v202
	v_mov_b32_e32 v125, v203
	s_nop 0
	v_mov_b32_e32 v170, v204
	v_mov_b32_e32 v171, v205
	v_mov_b32_e32 v172, v206
	v_mov_b32_e32 v173, v207
	v_lshlrev_b32_e32 v136, 6, v168
	v_and_b32_e32 v136, 0x1fbc0, v136
	v_lshl_add_u64 v[152:153], v[138:139], 0, v[136:137]
	v_cndmask_b32_e64 v125, 0, v125, s[4:5]
	v_cndmask_b32_e64 v123, 0, v123, s[4:5]
	v_cndmask_b32_e64 v173, 0, v173, s[4:5]
	v_cndmask_b32_e64 v171, 0, v171, s[4:5]
	v_mov_b32_e32 v136, v123
	v_mov_b32_e32 v174, v125
	v_mov_b32_e32 v176, v171
	v_mov_b32_e32 v178, v173
	v_cndmask_b32_e64 v124, 1.0, v124, s[4:5]
	v_cndmask_b32_e64 v122, 1.0, v122, s[4:5]
	v_cndmask_b32_e64 v172, 1.0, v172, s[4:5]
	v_cndmask_b32_e64 v170, 1.0, v170, s[4:5]
	v_pk_mul_f32 v[180:181], v[116:117], v[136:137] op_sel:[1,0] op_sel_hi:[0,0]
	v_pk_mul_f32 v[174:175], v[118:119], v[174:175] op_sel:[1,0] op_sel_hi:[0,0]
	v_pk_mul_f32 v[176:177], v[112:113], v[176:177] op_sel:[1,0] op_sel_hi:[0,0]
	v_pk_mul_f32 v[178:179], v[114:115], v[178:179] op_sel:[1,0] op_sel_hi:[0,0]
	v_pk_fma_f32 v[184:185], v[116:117], v[122:123], v[180:181] neg_lo:[0,0,1] neg_hi:[0,0,1]
	v_pk_fma_f32 v[116:117], v[116:117], v[122:123], v[180:181] op_sel_hi:[1,0,1]
	v_pk_fma_f32 v[122:123], v[118:119], v[124:125], v[174:175] neg_lo:[0,0,1] neg_hi:[0,0,1]
	v_pk_fma_f32 v[118:119], v[118:119], v[124:125], v[174:175] op_sel_hi:[1,0,1]
	v_pk_fma_f32 v[124:125], v[112:113], v[170:171], v[176:177] neg_lo:[0,0,1] neg_hi:[0,0,1]
	v_pk_fma_f32 v[170:171], v[112:113], v[170:171], v[176:177] op_sel_hi:[1,0,1]
	v_pk_fma_f32 v[174:175], v[114:115], v[172:173], v[178:179] neg_lo:[0,0,1] neg_hi:[0,0,1]
	v_pk_fma_f32 v[114:115], v[114:115], v[172:173], v[178:179] op_sel_hi:[1,0,1]
	v_cvt_pk_bf16_f32 v112, v184, v117
	v_cvt_pk_bf16_f32 v113, v122, v119
	v_cvt_pk_bf16_f32 v114, v124, v171
	v_cvt_pk_bf16_f32 v115, v174, v115
	global_store_dwordx4 v[126:127], v[112:115], off offset:256
	s_nop 1
	v_mov_b32_e32 v112, v208
	v_mov_b32_e32 v113, v209
	v_mov_b32_e32 v114, v210
	v_mov_b32_e32 v115, v211
	s_nop 0
	v_mov_b32_e32 v116, v212
	v_mov_b32_e32 v117, v213
	v_mov_b32_e32 v118, v214
	v_mov_b32_e32 v119, v215
	v_mad_i64_i32 v[122:123], s[0:1], v168, s68, v[120:121]
	v_lshl_add_u64 v[122:123], v[122:123], 0, v[150:151]
	v_cndmask_b32_e64 v115, 0, v115, s[4:5]
	v_cndmask_b32_e64 v113, 0, v113, s[4:5]
	v_cndmask_b32_e64 v119, 0, v119, s[4:5]
	v_cndmask_b32_e64 v117, 0, v117, s[4:5]
	v_mov_b32_e32 v124, v113
	v_mov_b32_e32 v126, v115
	v_mov_b32_e32 v136, v117
	v_mov_b32_e32 v168, v119
	v_cndmask_b32_e64 v114, 1.0, v114, s[4:5]
	v_cndmask_b32_e64 v112, 1.0, v112, s[4:5]
	v_cndmask_b32_e64 v118, 1.0, v118, s[4:5]
	v_cndmask_b32_e64 v116, 1.0, v116, s[4:5]
	v_pk_mul_f32 v[124:125], v[56:57], v[124:125] op_sel:[1,0] op_sel_hi:[0,0]
	v_pk_mul_f32 v[126:127], v[58:59], v[126:127] op_sel:[1,0] op_sel_hi:[0,0]
	v_pk_mul_f32 v[170:171], v[20:21], v[136:137] op_sel:[1,0] op_sel_hi:[0,0]
	v_pk_mul_f32 v[168:169], v[22:23], v[168:169] op_sel:[1,0] op_sel_hi:[0,0]
	v_pk_fma_f32 v[172:173], v[56:57], v[112:113], v[124:125] neg_lo:[0,0,1] neg_hi:[0,0,1]
	v_pk_fma_f32 v[112:113], v[56:57], v[112:113], v[124:125] op_sel_hi:[1,0,1]
	v_pk_fma_f32 v[124:125], v[58:59], v[114:115], v[126:127] neg_lo:[0,0,1] neg_hi:[0,0,1]
	v_pk_fma_f32 v[114:115], v[58:59], v[114:115], v[126:127] op_sel_hi:[1,0,1]
	v_pk_fma_f32 v[126:127], v[20:21], v[116:117], v[170:171] neg_lo:[0,0,1] neg_hi:[0,0,1]
	v_pk_fma_f32 v[116:117], v[20:21], v[116:117], v[170:171] op_sel_hi:[1,0,1]
	v_pk_fma_f32 v[170:171], v[22:23], v[118:119], v[168:169] neg_lo:[0,0,1] neg_hi:[0,0,1]
	v_pk_fma_f32 v[118:119], v[22:23], v[118:119], v[168:169] op_sel_hi:[1,0,1]
	v_cvt_pk_bf16_f32 v112, v172, v113
	v_cvt_pk_bf16_f32 v113, v124, v115
	v_cvt_pk_bf16_f32 v114, v126, v117
	v_cvt_pk_bf16_f32 v115, v170, v119
	global_store_dwordx4 v[122:123], v[112:115], off
	s_nop 1
	v_mov_b32_e32 v112, v208
	v_mov_b32_e32 v113, v209
	v_mov_b32_e32 v114, v210
	v_mov_b32_e32 v115, v211
	s_nop 0
	v_mov_b32_e32 v116, v212
	v_mov_b32_e32 v117, v213
	v_mov_b32_e32 v118, v214
	v_mov_b32_e32 v119, v215
	v_lshlrev_b32_e32 v124, 6, v167
	v_and_b32_e32 v136, 0x1ffc0, v124
	v_lshl_add_u64 v[124:125], v[138:139], 0, v[136:137]
	v_cndmask_b32_e64 v115, 0, v115, s[4:5]
	v_cndmask_b32_e64 v113, 0, v113, s[4:5]
	v_cndmask_b32_e64 v119, 0, v119, s[4:5]
	v_cndmask_b32_e64 v117, 0, v117, s[4:5]
	v_mov_b32_e32 v126, v113
	v_mov_b32_e32 v136, v115
	v_mov_b32_e32 v152, v117
	v_mov_b32_e32 v168, v119
	v_cndmask_b32_e64 v114, 1.0, v114, s[4:5]
	v_cndmask_b32_e64 v112, 1.0, v112, s[4:5]
	v_cndmask_b32_e64 v118, 1.0, v118, s[4:5]
	v_cndmask_b32_e64 v116, 1.0, v116, s[4:5]
	v_pk_mul_f32 v[126:127], v[108:109], v[126:127] op_sel:[1,0] op_sel_hi:[0,0]
	v_pk_mul_f32 v[170:171], v[110:111], v[136:137] op_sel:[1,0] op_sel_hi:[0,0]
	v_pk_mul_f32 v[152:153], v[104:105], v[152:153] op_sel:[1,0] op_sel_hi:[0,0]
	v_pk_mul_f32 v[168:169], v[106:107], v[168:169] op_sel:[1,0] op_sel_hi:[0,0]
	v_pk_fma_f32 v[172:173], v[108:109], v[112:113], v[126:127] neg_lo:[0,0,1] neg_hi:[0,0,1]
	v_pk_fma_f32 v[108:109], v[108:109], v[112:113], v[126:127] op_sel_hi:[1,0,1]
	v_pk_fma_f32 v[112:113], v[110:111], v[114:115], v[170:171] neg_lo:[0,0,1] neg_hi:[0,0,1]
	v_pk_fma_f32 v[110:111], v[110:111], v[114:115], v[170:171] op_sel_hi:[1,0,1]
	v_pk_fma_f32 v[114:115], v[104:105], v[116:117], v[152:153] neg_lo:[0,0,1] neg_hi:[0,0,1]
	v_pk_fma_f32 v[116:117], v[104:105], v[116:117], v[152:153] op_sel_hi:[1,0,1]
	v_pk_fma_f32 v[126:127], v[106:107], v[118:119], v[168:169] neg_lo:[0,0,1] neg_hi:[0,0,1]
	v_pk_fma_f32 v[106:107], v[106:107], v[118:119], v[168:169] op_sel_hi:[1,0,1]
	v_cvt_pk_bf16_f32 v104, v172, v109
	v_cvt_pk_bf16_f32 v105, v112, v111
	v_cvt_pk_bf16_f32 v106, v114, v117
	v_cvt_pk_bf16_f32 v107, v126, v107
	global_store_dwordx4 v[122:123], v[104:107], off offset:256
	s_nop 1
	v_mov_b32_e32 v104, v216
	v_mov_b32_e32 v105, v217
	v_mov_b32_e32 v106, v218
	v_mov_b32_e32 v107, v219
	s_nop 0
	v_mov_b32_e32 v108, v220
	v_mov_b32_e32 v109, v221
	v_mov_b32_e32 v110, v222
	v_mov_b32_e32 v111, v223
	v_mad_i64_i32 v[112:113], s[0:1], v167, s68, v[120:121]
	v_lshl_add_u64 v[112:113], v[112:113], 0, v[150:151]
	v_cndmask_b32_e64 v107, 0, v107, s[4:5]
	v_cndmask_b32_e64 v105, 0, v105, s[4:5]
	v_cndmask_b32_e64 v111, 0, v111, s[4:5]
	v_cndmask_b32_e64 v109, 0, v109, s[4:5]
	v_mov_b32_e32 v114, v105
	v_mov_b32_e32 v116, v107
	v_mov_b32_e32 v118, v109
	v_mov_b32_e32 v122, v111
	v_cndmask_b32_e64 v106, 1.0, v106, s[4:5]
	v_cndmask_b32_e64 v104, 1.0, v104, s[4:5]
	v_cndmask_b32_e64 v110, 1.0, v110, s[4:5]
	v_cndmask_b32_e64 v108, 1.0, v108, s[4:5]
	v_pk_mul_f32 v[114:115], v[52:53], v[114:115] op_sel:[1,0] op_sel_hi:[0,0]
	v_pk_mul_f32 v[116:117], v[54:55], v[116:117] op_sel:[1,0] op_sel_hi:[0,0]
	v_pk_mul_f32 v[118:119], v[16:17], v[118:119] op_sel:[1,0] op_sel_hi:[0,0]
	v_pk_mul_f32 v[122:123], v[18:19], v[122:123] op_sel:[1,0] op_sel_hi:[0,0]
	v_pk_fma_f32 v[126:127], v[52:53], v[104:105], v[114:115] neg_lo:[0,0,1] neg_hi:[0,0,1]
	v_pk_fma_f32 v[104:105], v[52:53], v[104:105], v[114:115] op_sel_hi:[1,0,1]
	v_pk_fma_f32 v[114:115], v[54:55], v[106:107], v[116:117] neg_lo:[0,0,1] neg_hi:[0,0,1]
	v_pk_fma_f32 v[106:107], v[54:55], v[106:107], v[116:117] op_sel_hi:[1,0,1]
	v_pk_fma_f32 v[116:117], v[16:17], v[108:109], v[118:119] neg_lo:[0,0,1] neg_hi:[0,0,1]
	v_pk_fma_f32 v[108:109], v[16:17], v[108:109], v[118:119] op_sel_hi:[1,0,1]
	v_pk_fma_f32 v[118:119], v[18:19], v[110:111], v[122:123] neg_lo:[0,0,1] neg_hi:[0,0,1]
	v_pk_fma_f32 v[110:111], v[18:19], v[110:111], v[122:123] op_sel_hi:[1,0,1]
	v_cvt_pk_bf16_f32 v104, v126, v105
	v_cvt_pk_bf16_f32 v105, v114, v107
	v_cvt_pk_bf16_f32 v106, v116, v109
	v_cvt_pk_bf16_f32 v107, v118, v111
	global_store_dwordx4 v[112:113], v[104:107], off
	s_nop 1
	v_mov_b32_e32 v104, v216
	v_mov_b32_e32 v105, v217
	v_mov_b32_e32 v106, v218
	v_mov_b32_e32 v107, v219
	s_nop 0
	v_mov_b32_e32 v108, v220
	v_mov_b32_e32 v109, v221
	v_mov_b32_e32 v110, v222
	v_mov_b32_e32 v111, v223
	v_lshlrev_b32_e32 v114, 6, v166
	v_and_b32_e32 v136, 0x1f3c0, v114
	v_lshl_add_u64 v[114:115], v[138:139], 0, v[136:137]
	v_cndmask_b32_e64 v107, 0, v107, s[4:5]
	v_cndmask_b32_e64 v105, 0, v105, s[4:5]
	v_cndmask_b32_e64 v111, 0, v111, s[4:5]
	v_cndmask_b32_e64 v109, 0, v109, s[4:5]
	v_mov_b32_e32 v116, v105
	v_mov_b32_e32 v118, v107
	v_mov_b32_e32 v122, v109
	v_mov_b32_e32 v124, v111
	v_cndmask_b32_e64 v106, 1.0, v106, s[4:5]
	v_cndmask_b32_e64 v104, 1.0, v104, s[4:5]
	v_cndmask_b32_e64 v110, 1.0, v110, s[4:5]
	v_cndmask_b32_e64 v108, 1.0, v108, s[4:5]
	v_pk_mul_f32 v[116:117], v[100:101], v[116:117] op_sel:[1,0] op_sel_hi:[0,0]
	v_pk_mul_f32 v[118:119], v[102:103], v[118:119] op_sel:[1,0] op_sel_hi:[0,0]
	v_pk_mul_f32 v[122:123], v[96:97], v[122:123] op_sel:[1,0] op_sel_hi:[0,0]
	v_pk_mul_f32 v[124:125], v[98:99], v[124:125] op_sel:[1,0] op_sel_hi:[0,0]
	v_pk_fma_f32 v[126:127], v[100:101], v[104:105], v[116:117] neg_lo:[0,0,1] neg_hi:[0,0,1]
	v_pk_fma_f32 v[100:101], v[100:101], v[104:105], v[116:117] op_sel_hi:[1,0,1]
	v_pk_fma_f32 v[104:105], v[102:103], v[106:107], v[118:119] neg_lo:[0,0,1] neg_hi:[0,0,1]
	v_pk_fma_f32 v[102:103], v[102:103], v[106:107], v[118:119] op_sel_hi:[1,0,1]
	v_pk_fma_f32 v[106:107], v[96:97], v[108:109], v[122:123] neg_lo:[0,0,1] neg_hi:[0,0,1]
	v_pk_fma_f32 v[108:109], v[96:97], v[108:109], v[122:123] op_sel_hi:[1,0,1]
	v_pk_fma_f32 v[116:117], v[98:99], v[110:111], v[124:125] neg_lo:[0,0,1] neg_hi:[0,0,1]
	v_pk_fma_f32 v[98:99], v[98:99], v[110:111], v[124:125] op_sel_hi:[1,0,1]
	v_cvt_pk_bf16_f32 v96, v126, v101
	v_cvt_pk_bf16_f32 v97, v104, v103
	v_cvt_pk_bf16_f32 v98, v106, v109
	v_cvt_pk_bf16_f32 v99, v116, v99
	global_store_dwordx4 v[112:113], v[96:99], off offset:256
	s_nop 1
	v_mov_b32_e32 v96, v224
	v_mov_b32_e32 v97, v225
	v_mov_b32_e32 v98, v226
	v_mov_b32_e32 v99, v227
	s_nop 0
	v_mov_b32_e32 v100, v228
	v_mov_b32_e32 v101, v229
	v_mov_b32_e32 v102, v230
	v_mov_b32_e32 v103, v231
	v_mad_i64_i32 v[104:105], s[0:1], v166, s68, v[120:121]
	v_lshl_add_u64 v[104:105], v[104:105], 0, v[150:151]
	v_cndmask_b32_e64 v99, 0, v99, s[4:5]
	v_cndmask_b32_e64 v97, 0, v97, s[4:5]
	v_cndmask_b32_e64 v103, 0, v103, s[4:5]
	v_cndmask_b32_e64 v101, 0, v101, s[4:5]
	v_mov_b32_e32 v106, v97
	v_mov_b32_e32 v108, v99
	v_mov_b32_e32 v110, v101
	v_mov_b32_e32 v112, v103
	v_cndmask_b32_e64 v98, 1.0, v98, s[4:5]
	v_cndmask_b32_e64 v96, 1.0, v96, s[4:5]
	v_cndmask_b32_e64 v102, 1.0, v102, s[4:5]
	v_cndmask_b32_e64 v100, 1.0, v100, s[4:5]
	v_pk_mul_f32 v[106:107], v[44:45], v[106:107] op_sel:[1,0] op_sel_hi:[0,0]
	v_pk_mul_f32 v[108:109], v[46:47], v[108:109] op_sel:[1,0] op_sel_hi:[0,0]
	v_pk_mul_f32 v[110:111], v[12:13], v[110:111] op_sel:[1,0] op_sel_hi:[0,0]
	v_pk_mul_f32 v[112:113], v[14:15], v[112:113] op_sel:[1,0] op_sel_hi:[0,0]
	v_pk_fma_f32 v[116:117], v[44:45], v[96:97], v[106:107] neg_lo:[0,0,1] neg_hi:[0,0,1]
	v_pk_fma_f32 v[96:97], v[44:45], v[96:97], v[106:107] op_sel_hi:[1,0,1]
	v_pk_fma_f32 v[106:107], v[46:47], v[98:99], v[108:109] neg_lo:[0,0,1] neg_hi:[0,0,1]
	v_pk_fma_f32 v[98:99], v[46:47], v[98:99], v[108:109] op_sel_hi:[1,0,1]
	v_pk_fma_f32 v[108:109], v[12:13], v[100:101], v[110:111] neg_lo:[0,0,1] neg_hi:[0,0,1]
	v_pk_fma_f32 v[100:101], v[12:13], v[100:101], v[110:111] op_sel_hi:[1,0,1]
	v_pk_fma_f32 v[110:111], v[14:15], v[102:103], v[112:113] neg_lo:[0,0,1] neg_hi:[0,0,1]
	v_pk_fma_f32 v[102:103], v[14:15], v[102:103], v[112:113] op_sel_hi:[1,0,1]
	v_cvt_pk_bf16_f32 v96, v116, v97
	v_cvt_pk_bf16_f32 v97, v106, v99
	v_cvt_pk_bf16_f32 v98, v108, v101
	v_cvt_pk_bf16_f32 v99, v110, v103
	global_store_dwordx4 v[104:105], v[96:99], off
	s_nop 1
	v_mov_b32_e32 v96, v224
	v_mov_b32_e32 v97, v225
	v_mov_b32_e32 v98, v226
	v_mov_b32_e32 v99, v227
	s_nop 0
	v_mov_b32_e32 v100, v228
	v_mov_b32_e32 v101, v229
	v_mov_b32_e32 v102, v230
	v_mov_b32_e32 v103, v231
	v_lshlrev_b32_e32 v106, 6, v165
	v_and_b32_e32 v136, 0x1f7c0, v106
	v_lshl_add_u64 v[106:107], v[138:139], 0, v[136:137]
	v_cndmask_b32_e64 v99, 0, v99, s[4:5]
	v_cndmask_b32_e64 v97, 0, v97, s[4:5]
	v_cndmask_b32_e64 v103, 0, v103, s[4:5]
	v_cndmask_b32_e64 v101, 0, v101, s[4:5]
	v_mov_b32_e32 v108, v97
	v_mov_b32_e32 v110, v99
	v_mov_b32_e32 v112, v101
	v_mov_b32_e32 v114, v103
	v_cndmask_b32_e64 v98, 1.0, v98, s[4:5]
	v_cndmask_b32_e64 v96, 1.0, v96, s[4:5]
	v_cndmask_b32_e64 v102, 1.0, v102, s[4:5]
	v_cndmask_b32_e64 v100, 1.0, v100, s[4:5]
	v_pk_mul_f32 v[108:109], v[92:93], v[108:109] op_sel:[1,0] op_sel_hi:[0,0]
	v_pk_mul_f32 v[110:111], v[94:95], v[110:111] op_sel:[1,0] op_sel_hi:[0,0]
	v_pk_mul_f32 v[112:113], v[88:89], v[112:113] op_sel:[1,0] op_sel_hi:[0,0]
	v_pk_mul_f32 v[114:115], v[90:91], v[114:115] op_sel:[1,0] op_sel_hi:[0,0]
	v_pk_fma_f32 v[116:117], v[92:93], v[96:97], v[108:109] neg_lo:[0,0,1] neg_hi:[0,0,1]
	v_pk_fma_f32 v[92:93], v[92:93], v[96:97], v[108:109] op_sel_hi:[1,0,1]
	v_pk_fma_f32 v[96:97], v[94:95], v[98:99], v[110:111] neg_lo:[0,0,1] neg_hi:[0,0,1]
	v_pk_fma_f32 v[94:95], v[94:95], v[98:99], v[110:111] op_sel_hi:[1,0,1]
	v_pk_fma_f32 v[98:99], v[88:89], v[100:101], v[112:113] neg_lo:[0,0,1] neg_hi:[0,0,1]
	v_pk_fma_f32 v[100:101], v[88:89], v[100:101], v[112:113] op_sel_hi:[1,0,1]
	v_pk_fma_f32 v[108:109], v[90:91], v[102:103], v[114:115] neg_lo:[0,0,1] neg_hi:[0,0,1]
	v_pk_fma_f32 v[90:91], v[90:91], v[102:103], v[114:115] op_sel_hi:[1,0,1]
	v_cvt_pk_bf16_f32 v88, v116, v93
	v_cvt_pk_bf16_f32 v89, v96, v95
	v_cvt_pk_bf16_f32 v90, v98, v101
	v_cvt_pk_bf16_f32 v91, v108, v91
	global_store_dwordx4 v[104:105], v[88:91], off offset:256
	s_nop 1
	v_mov_b32_e32 v88, v232
	v_mov_b32_e32 v89, v233
	v_mov_b32_e32 v90, v234
	v_mov_b32_e32 v91, v235
	s_nop 0
	v_mov_b32_e32 v92, v236
	v_mov_b32_e32 v93, v237
	v_mov_b32_e32 v94, v238
	v_mov_b32_e32 v95, v239
	v_mad_i64_i32 v[96:97], s[0:1], v165, s68, v[120:121]
	v_lshl_add_u64 v[96:97], v[96:97], 0, v[150:151]
	v_cndmask_b32_e64 v91, 0, v91, s[4:5]
	v_cndmask_b32_e64 v89, 0, v89, s[4:5]
	v_cndmask_b32_e64 v95, 0, v95, s[4:5]
	v_cndmask_b32_e64 v93, 0, v93, s[4:5]
	v_mov_b32_e32 v98, v89
	v_mov_b32_e32 v100, v91
	v_mov_b32_e32 v102, v93
	v_mov_b32_e32 v104, v95
	v_cndmask_b32_e64 v90, 1.0, v90, s[4:5]
	v_cndmask_b32_e64 v88, 1.0, v88, s[4:5]
	v_cndmask_b32_e64 v94, 1.0, v94, s[4:5]
	v_cndmask_b32_e64 v92, 1.0, v92, s[4:5]
	v_pk_mul_f32 v[98:99], v[40:41], v[98:99] op_sel:[1,0] op_sel_hi:[0,0]
	v_pk_mul_f32 v[100:101], v[42:43], v[100:101] op_sel:[1,0] op_sel_hi:[0,0]
	v_pk_mul_f32 v[102:103], v[8:9], v[102:103] op_sel:[1,0] op_sel_hi:[0,0]
	v_pk_mul_f32 v[104:105], v[10:11], v[104:105] op_sel:[1,0] op_sel_hi:[0,0]
	v_pk_fma_f32 v[108:109], v[40:41], v[88:89], v[98:99] neg_lo:[0,0,1] neg_hi:[0,0,1]
	v_pk_fma_f32 v[88:89], v[40:41], v[88:89], v[98:99] op_sel_hi:[1,0,1]
	v_pk_fma_f32 v[98:99], v[42:43], v[90:91], v[100:101] neg_lo:[0,0,1] neg_hi:[0,0,1]
	v_pk_fma_f32 v[90:91], v[42:43], v[90:91], v[100:101] op_sel_hi:[1,0,1]
	v_pk_fma_f32 v[100:101], v[8:9], v[92:93], v[102:103] neg_lo:[0,0,1] neg_hi:[0,0,1]
	v_pk_fma_f32 v[92:93], v[8:9], v[92:93], v[102:103] op_sel_hi:[1,0,1]
	v_pk_fma_f32 v[102:103], v[10:11], v[94:95], v[104:105] neg_lo:[0,0,1] neg_hi:[0,0,1]
	v_pk_fma_f32 v[94:95], v[10:11], v[94:95], v[104:105] op_sel_hi:[1,0,1]
	v_cvt_pk_bf16_f32 v88, v108, v89
	v_cvt_pk_bf16_f32 v89, v98, v91
	v_cvt_pk_bf16_f32 v90, v100, v93
	v_cvt_pk_bf16_f32 v91, v102, v95
	global_store_dwordx4 v[96:97], v[88:91], off
	s_nop 1
	v_mov_b32_e32 v88, v232
	v_mov_b32_e32 v89, v233
	v_mov_b32_e32 v90, v234
	v_mov_b32_e32 v91, v235
	s_nop 0
	v_mov_b32_e32 v92, v236
	v_mov_b32_e32 v93, v237
	v_mov_b32_e32 v94, v238
	v_mov_b32_e32 v95, v239
	v_lshlrev_b32_e32 v98, 6, v164
	v_and_b32_e32 v136, 0x1fbc0, v98
	v_lshl_add_u64 v[98:99], v[138:139], 0, v[136:137]
	v_cndmask_b32_e64 v91, 0, v91, s[4:5]
	v_cndmask_b32_e64 v89, 0, v89, s[4:5]
	v_cndmask_b32_e64 v95, 0, v95, s[4:5]
	v_cndmask_b32_e64 v93, 0, v93, s[4:5]
	v_mov_b32_e32 v100, v89
	v_mov_b32_e32 v102, v91
	v_mov_b32_e32 v104, v93
	v_mov_b32_e32 v106, v95
	v_cndmask_b32_e64 v90, 1.0, v90, s[4:5]
	v_cndmask_b32_e64 v88, 1.0, v88, s[4:5]
	v_cndmask_b32_e64 v94, 1.0, v94, s[4:5]
	v_cndmask_b32_e64 v92, 1.0, v92, s[4:5]
	v_pk_mul_f32 v[100:101], v[84:85], v[100:101] op_sel:[1,0] op_sel_hi:[0,0]
	v_pk_mul_f32 v[102:103], v[86:87], v[102:103] op_sel:[1,0] op_sel_hi:[0,0]
	v_pk_mul_f32 v[104:105], v[80:81], v[104:105] op_sel:[1,0] op_sel_hi:[0,0]
	v_pk_mul_f32 v[106:107], v[82:83], v[106:107] op_sel:[1,0] op_sel_hi:[0,0]
	v_pk_fma_f32 v[108:109], v[84:85], v[88:89], v[100:101] neg_lo:[0,0,1] neg_hi:[0,0,1]
	v_pk_fma_f32 v[84:85], v[84:85], v[88:89], v[100:101] op_sel_hi:[1,0,1]
	v_pk_fma_f32 v[88:89], v[86:87], v[90:91], v[102:103] neg_lo:[0,0,1] neg_hi:[0,0,1]
	v_pk_fma_f32 v[86:87], v[86:87], v[90:91], v[102:103] op_sel_hi:[1,0,1]
	v_pk_fma_f32 v[90:91], v[80:81], v[92:93], v[104:105] neg_lo:[0,0,1] neg_hi:[0,0,1]
	v_pk_fma_f32 v[92:93], v[80:81], v[92:93], v[104:105] op_sel_hi:[1,0,1]
	v_pk_fma_f32 v[100:101], v[82:83], v[94:95], v[106:107] neg_lo:[0,0,1] neg_hi:[0,0,1]
	v_pk_fma_f32 v[82:83], v[82:83], v[94:95], v[106:107] op_sel_hi:[1,0,1]
	v_cvt_pk_bf16_f32 v80, v108, v85
	v_cvt_pk_bf16_f32 v81, v88, v87
	v_cvt_pk_bf16_f32 v82, v90, v93
	v_cvt_pk_bf16_f32 v83, v100, v83
	global_store_dwordx4 v[96:97], v[80:83], off offset:256
	s_nop 1
	v_mov_b32_e32 v80, v240
	v_mov_b32_e32 v81, v241
	v_mov_b32_e32 v82, v242
	v_mov_b32_e32 v83, v243
	s_nop 0
	v_mov_b32_e32 v84, v244
	v_mov_b32_e32 v85, v245
	v_mov_b32_e32 v86, v246
	v_mov_b32_e32 v87, v247
	v_mad_i64_i32 v[88:89], s[0:1], v164, s68, v[120:121]
	v_lshl_add_u64 v[88:89], v[88:89], 0, v[150:151]
	v_cndmask_b32_e64 v83, 0, v83, s[4:5]
	v_cndmask_b32_e64 v81, 0, v81, s[4:5]
	v_cndmask_b32_e64 v87, 0, v87, s[4:5]
	v_cndmask_b32_e64 v85, 0, v85, s[4:5]
	v_mov_b32_e32 v90, v81
	v_mov_b32_e32 v92, v83
	v_mov_b32_e32 v94, v85
	v_mov_b32_e32 v96, v87
	v_cndmask_b32_e64 v82, 1.0, v82, s[4:5]
	v_cndmask_b32_e64 v80, 1.0, v80, s[4:5]
	v_cndmask_b32_e64 v86, 1.0, v86, s[4:5]
	v_cndmask_b32_e64 v84, 1.0, v84, s[4:5]
	v_pk_mul_f32 v[90:91], v[36:37], v[90:91] op_sel:[1,0] op_sel_hi:[0,0]
	v_pk_mul_f32 v[92:93], v[38:39], v[92:93] op_sel:[1,0] op_sel_hi:[0,0]
	v_pk_mul_f32 v[94:95], v[4:5], v[94:95] op_sel:[1,0] op_sel_hi:[0,0]
	v_pk_mul_f32 v[96:97], v[6:7], v[96:97] op_sel:[1,0] op_sel_hi:[0,0]
	v_pk_fma_f32 v[100:101], v[36:37], v[80:81], v[90:91] neg_lo:[0,0,1] neg_hi:[0,0,1]
	v_pk_fma_f32 v[80:81], v[36:37], v[80:81], v[90:91] op_sel_hi:[1,0,1]
	v_pk_fma_f32 v[90:91], v[38:39], v[82:83], v[92:93] neg_lo:[0,0,1] neg_hi:[0,0,1]
	v_pk_fma_f32 v[82:83], v[38:39], v[82:83], v[92:93] op_sel_hi:[1,0,1]
	v_pk_fma_f32 v[92:93], v[4:5], v[84:85], v[94:95] neg_lo:[0,0,1] neg_hi:[0,0,1]
	v_pk_fma_f32 v[84:85], v[4:5], v[84:85], v[94:95] op_sel_hi:[1,0,1]
	v_pk_fma_f32 v[94:95], v[6:7], v[86:87], v[96:97] neg_lo:[0,0,1] neg_hi:[0,0,1]
	v_pk_fma_f32 v[86:87], v[6:7], v[86:87], v[96:97] op_sel_hi:[1,0,1]
	v_cvt_pk_bf16_f32 v80, v100, v81
	v_cvt_pk_bf16_f32 v81, v90, v83
	v_cvt_pk_bf16_f32 v82, v92, v85
	v_cvt_pk_bf16_f32 v83, v94, v87
	global_store_dwordx4 v[88:89], v[80:83], off
	s_nop 1
	v_mov_b32_e32 v80, v240
	v_mov_b32_e32 v81, v241
	v_mov_b32_e32 v82, v242
	v_mov_b32_e32 v83, v243
	s_nop 0
	v_mov_b32_e32 v84, v244
	v_mov_b32_e32 v85, v245
	v_mov_b32_e32 v86, v246
	v_mov_b32_e32 v87, v247
	v_lshlrev_b32_e32 v90, 6, v163
	v_and_b32_e32 v136, 0x1ffc0, v90
	v_lshl_add_u64 v[90:91], v[138:139], 0, v[136:137]
	v_cndmask_b32_e64 v83, 0, v83, s[4:5]
	v_cndmask_b32_e64 v81, 0, v81, s[4:5]
	v_cndmask_b32_e64 v87, 0, v87, s[4:5]
	v_cndmask_b32_e64 v85, 0, v85, s[4:5]
	v_mov_b32_e32 v92, v81
	v_mov_b32_e32 v94, v83
	v_mov_b32_e32 v96, v85
	v_mov_b32_e32 v98, v87
	v_cndmask_b32_e64 v82, 1.0, v82, s[4:5]
	v_cndmask_b32_e64 v80, 1.0, v80, s[4:5]
	v_cndmask_b32_e64 v86, 1.0, v86, s[4:5]
	v_cndmask_b32_e64 v84, 1.0, v84, s[4:5]
	v_pk_mul_f32 v[92:93], v[76:77], v[92:93] op_sel:[1,0] op_sel_hi:[0,0]
	v_pk_mul_f32 v[94:95], v[78:79], v[94:95] op_sel:[1,0] op_sel_hi:[0,0]
	v_pk_mul_f32 v[96:97], v[72:73], v[96:97] op_sel:[1,0] op_sel_hi:[0,0]
	v_pk_mul_f32 v[98:99], v[74:75], v[98:99] op_sel:[1,0] op_sel_hi:[0,0]
	v_pk_fma_f32 v[100:101], v[76:77], v[80:81], v[92:93] neg_lo:[0,0,1] neg_hi:[0,0,1]
	v_pk_fma_f32 v[76:77], v[76:77], v[80:81], v[92:93] op_sel_hi:[1,0,1]
	v_pk_fma_f32 v[80:81], v[78:79], v[82:83], v[94:95] neg_lo:[0,0,1] neg_hi:[0,0,1]
	v_pk_fma_f32 v[78:79], v[78:79], v[82:83], v[94:95] op_sel_hi:[1,0,1]
	v_pk_fma_f32 v[82:83], v[72:73], v[84:85], v[96:97] neg_lo:[0,0,1] neg_hi:[0,0,1]
	v_pk_fma_f32 v[84:85], v[72:73], v[84:85], v[96:97] op_sel_hi:[1,0,1]
	v_pk_fma_f32 v[92:93], v[74:75], v[86:87], v[98:99] neg_lo:[0,0,1] neg_hi:[0,0,1]
	v_pk_fma_f32 v[74:75], v[74:75], v[86:87], v[98:99] op_sel_hi:[1,0,1]
	v_cvt_pk_bf16_f32 v72, v100, v77
	v_cvt_pk_bf16_f32 v73, v80, v79
	v_cvt_pk_bf16_f32 v74, v82, v85
	v_cvt_pk_bf16_f32 v75, v92, v75
	global_store_dwordx4 v[88:89], v[72:75], off offset:256
	s_nop 1
	v_mov_b32_e32 v72, v248
	v_mov_b32_e32 v73, v249
	v_mov_b32_e32 v74, v250
	v_mov_b32_e32 v75, v251
	s_nop 0
	v_mov_b32_e32 v76, v252
	v_mov_b32_e32 v77, v253
	v_mov_b32_e32 v78, v183
	v_mov_b32_e32 v79, v255
	v_mad_i64_i32 v[80:81], s[0:1], v163, s68, v[120:121]
	v_lshl_add_u64 v[80:81], v[80:81], 0, v[150:151]
	v_cndmask_b32_e64 v75, 0, v75, s[4:5]
	v_cndmask_b32_e64 v73, 0, v73, s[4:5]
	v_cndmask_b32_e64 v79, 0, v79, s[4:5]
	v_cndmask_b32_e64 v77, 0, v77, s[4:5]
	v_mov_b32_e32 v82, v73
	v_mov_b32_e32 v84, v75
	v_mov_b32_e32 v86, v77
	v_mov_b32_e32 v88, v79
	v_cndmask_b32_e64 v74, 1.0, v74, s[4:5]
	v_cndmask_b32_e64 v72, 1.0, v72, s[4:5]
	v_cndmask_b32_e64 v78, 1.0, v78, s[4:5]
	v_cndmask_b32_e64 v76, 1.0, v76, s[4:5]
	v_pk_mul_f32 v[82:83], v[32:33], v[82:83] op_sel:[1,0] op_sel_hi:[0,0]
	v_pk_mul_f32 v[84:85], v[34:35], v[84:85] op_sel:[1,0] op_sel_hi:[0,0]
	v_pk_mul_f32 v[86:87], v[0:1], v[86:87] op_sel:[1,0] op_sel_hi:[0,0]
	v_pk_mul_f32 v[88:89], v[2:3], v[88:89] op_sel:[1,0] op_sel_hi:[0,0]
	v_pk_fma_f32 v[92:93], v[32:33], v[72:73], v[82:83] neg_lo:[0,0,1] neg_hi:[0,0,1]
	v_pk_fma_f32 v[72:73], v[32:33], v[72:73], v[82:83] op_sel_hi:[1,0,1]
	v_pk_fma_f32 v[82:83], v[34:35], v[74:75], v[84:85] neg_lo:[0,0,1] neg_hi:[0,0,1]
	v_pk_fma_f32 v[74:75], v[34:35], v[74:75], v[84:85] op_sel_hi:[1,0,1]
	v_pk_fma_f32 v[84:85], v[0:1], v[76:77], v[86:87] neg_lo:[0,0,1] neg_hi:[0,0,1]
	v_pk_fma_f32 v[76:77], v[0:1], v[76:77], v[86:87] op_sel_hi:[1,0,1]
	v_pk_fma_f32 v[86:87], v[2:3], v[78:79], v[88:89] neg_lo:[0,0,1] neg_hi:[0,0,1]
	v_pk_fma_f32 v[78:79], v[2:3], v[78:79], v[88:89] op_sel_hi:[1,0,1]
	v_cvt_pk_bf16_f32 v72, v92, v73
	v_cvt_pk_bf16_f32 v73, v82, v75
	v_cvt_pk_bf16_f32 v74, v84, v77
	v_cvt_pk_bf16_f32 v75, v86, v79
	global_store_dwordx4 v[80:81], v[72:75], off
	s_nop 1
	v_mov_b32_e32 v72, v248
	v_mov_b32_e32 v73, v249
	v_mov_b32_e32 v74, v250
	v_mov_b32_e32 v75, v251
	s_nop 0
	v_mov_b32_e32 v76, v252
	v_mov_b32_e32 v77, v253
	v_mov_b32_e32 v78, v183
	v_mov_b32_e32 v79, v255
	v_cndmask_b32_e64 v75, 0, v75, s[4:5]
	v_cndmask_b32_e64 v73, 0, v73, s[4:5]
	v_cndmask_b32_e64 v79, 0, v79, s[4:5]
	v_cndmask_b32_e64 v77, 0, v77, s[4:5]
	v_mov_b32_e32 v82, v73
	v_mov_b32_e32 v84, v75
	v_mov_b32_e32 v86, v77
	v_mov_b32_e32 v88, v79
	v_cndmask_b32_e64 v74, 1.0, v74, s[4:5]
	v_cndmask_b32_e64 v72, 1.0, v72, s[4:5]
	v_cndmask_b32_e64 v78, 1.0, v78, s[4:5]
	v_cndmask_b32_e64 v76, 1.0, v76, s[4:5]
	v_pk_mul_f32 v[82:83], v[68:69], v[82:83] op_sel:[1,0] op_sel_hi:[0,0]
	v_pk_mul_f32 v[84:85], v[70:71], v[84:85] op_sel:[1,0] op_sel_hi:[0,0]
	v_pk_mul_f32 v[86:87], v[48:49], v[86:87] op_sel:[1,0] op_sel_hi:[0,0]
	v_pk_mul_f32 v[88:89], v[50:51], v[88:89] op_sel:[1,0] op_sel_hi:[0,0]
	v_pk_fma_f32 v[90:91], v[68:69], v[72:73], v[82:83] neg_lo:[0,0,1] neg_hi:[0,0,1]
	v_pk_fma_f32 v[68:69], v[68:69], v[72:73], v[82:83] op_sel_hi:[1,0,1]
	v_pk_fma_f32 v[72:73], v[70:71], v[74:75], v[84:85] neg_lo:[0,0,1] neg_hi:[0,0,1]
	v_pk_fma_f32 v[70:71], v[70:71], v[74:75], v[84:85] op_sel_hi:[1,0,1]
	v_pk_fma_f32 v[74:75], v[48:49], v[76:77], v[86:87] neg_lo:[0,0,1] neg_hi:[0,0,1]
	v_pk_fma_f32 v[76:77], v[48:49], v[76:77], v[86:87] op_sel_hi:[1,0,1]
	v_pk_fma_f32 v[82:83], v[50:51], v[78:79], v[88:89] neg_lo:[0,0,1] neg_hi:[0,0,1]
	v_pk_fma_f32 v[50:51], v[50:51], v[78:79], v[88:89] op_sel_hi:[1,0,1]
	v_cvt_pk_bf16_f32 v48, v90, v69
	v_cvt_pk_bf16_f32 v49, v72, v71
	v_cvt_pk_bf16_f32 v50, v74, v77
	v_cvt_pk_bf16_f32 v51, v82, v51
	global_store_dwordx4 v[80:81], v[48:51], off offset:256
